# down-GEMM epilogue rewritten as a 16-deep software pipeline (load / add / store per quad, counted vmcnt, SGPR-base addressing)
# speedup vs baseline: 1.0010x; 1.0010x over previous
;     __device__ __forceinline__ void operator()(const f32x4 (&acc)[2][2][4][2], const Unit& u, int wr, int wc, int fr, int fq) const {
;         const int row0 = u.pm * BM + wr * 64 + fr, c0 = u.pn * BM + wc * 32 + 4 * fq;
; #pragma unroll
;         for (int ai = 0; ai < 2; ++ai) {
;             f32x4 b[4][2][2];
; #pragma unroll
;             for (int m = 0; m < 4; ++m)
; #pragma unroll
;                 for (int bj = 0; bj < 2; ++bj)
; #pragma unroll
;                     for (int n = 0; n < 2; ++n) b[m][bj][n] = __builtin_nontemporal_load((const f32x4*)(base + (size_t)(row0 + ai * HALF + m * 16) * ldc + c0 + bj * HALF + n * 16));
; #pragma unroll
;             for (int m = 0; m < 4; ++m) {
;                 const size_t off = (size_t)(row0 + ai * HALF + m * 16) * ldc + c0;
; #pragma unroll
;                 for (int bj = 0; bj < 2; ++bj)
; #pragma unroll
;                     for (int n = 0; n < 2; ++n) {
;                         if (nt_store) __builtin_nontemporal_store(b[m][bj][n] + acc[ai][bj][m][n], (f32x4*)(out + off + bj * HALF + n * 16));
;                         else *(f32x4*)(out + off + bj * HALF + n * 16) = b[m][bj][n] + acc[ai][bj][m][n]; }
.LBB0_1101:
	v_lshl_or_b32 v140, s51, 8, v154
	v_lshl_add_u32 v150, s50, 8, v152
	v_lshlrev_b32_e32 v140, 2, v140
	v_lshl_add_u32 v140, v150, 13, v140
	v_or_b32_e32 v141, 0x20000, v140
	v_or_b32_e32 v142, 0x40000, v140
	v_or_b32_e32 v143, 0x60000, v140
	v_add_u32_e32 v144, 0x100000, v140
	v_add_u32_e32 v145, 0x120000, v140
	v_add_u32_e32 v150, 0x140000, v140
	v_add_u32_e32 v151, 0x160000, v140
	global_load_dwordx4 v[146:149], v140, s[28:29] nt
	global_load_dwordx4 v[158:161], v140, s[28:29] offset:64 nt
	global_load_dwordx4 v[162:165], v140, s[28:29] offset:512 nt
	global_load_dwordx4 v[166:169], v140, s[28:29] offset:576 nt
	global_load_dwordx4 v[170:173], v141, s[28:29] nt
	global_load_dwordx4 v[174:177], v141, s[28:29] offset:64 nt
	global_load_dwordx4 v[178:181], v141, s[28:29] offset:512 nt
	global_load_dwordx4 v[182:185], v141, s[28:29] offset:576 nt
	global_load_dwordx4 v[186:189], v142, s[28:29] nt
	global_load_dwordx4 v[190:193], v142, s[28:29] offset:64 nt
	global_load_dwordx4 v[194:197], v142, s[28:29] offset:512 nt
	global_load_dwordx4 v[198:201], v142, s[28:29] offset:576 nt
	global_load_dwordx4 v[202:205], v143, s[28:29] nt
	global_load_dwordx4 v[206:209], v143, s[28:29] offset:64 nt
	global_load_dwordx4 v[210:213], v143, s[28:29] offset:512 nt
	global_load_dwordx4 v[214:217], v143, s[28:29] offset:576 nt
	s_waitcnt vmcnt(15)
	v_pk_add_f32 v[124:125], v[124:125], v[146:147]
	v_pk_add_f32 v[126:127], v[126:127], v[148:149]
	global_store_dwordx4 v140, v[124:127], s[28:29]
	global_load_dwordx4 v[146:149], v144, s[28:29] nt
	s_waitcnt vmcnt(16)
	v_pk_add_f32 v[120:121], v[120:121], v[158:159]
	v_pk_add_f32 v[122:123], v[122:123], v[160:161]
	global_store_dwordx4 v140, v[120:123], s[28:29] offset:64
	global_load_dwordx4 v[158:161], v144, s[28:29] offset:64 nt
	s_waitcnt vmcnt(17)
	v_pk_add_f32 v[108:109], v[108:109], v[162:163]
	v_pk_add_f32 v[110:111], v[110:111], v[164:165]
	global_store_dwordx4 v140, v[108:111], s[28:29] offset:512
	global_load_dwordx4 v[162:165], v144, s[28:29] offset:512 nt
	s_waitcnt vmcnt(18)
	v_pk_add_f32 v[100:101], v[100:101], v[166:167]
	v_pk_add_f32 v[102:103], v[102:103], v[168:169]
	global_store_dwordx4 v140, v[100:103], s[28:29] offset:576
	global_load_dwordx4 v[166:169], v144, s[28:29] offset:576 nt
	s_waitcnt vmcnt(19)
	v_pk_add_f32 v[116:117], v[116:117], v[170:171]
	v_pk_add_f32 v[118:119], v[118:119], v[172:173]
	global_store_dwordx4 v141, v[116:119], s[28:29]
	global_load_dwordx4 v[170:173], v145, s[28:29] nt
	s_waitcnt vmcnt(20)
	v_pk_add_f32 v[112:113], v[112:113], v[174:175]
	v_pk_add_f32 v[114:115], v[114:115], v[176:177]
	global_store_dwordx4 v141, v[112:115], s[28:29] offset:64
	global_load_dwordx4 v[174:177], v145, s[28:29] offset:64 nt
	s_waitcnt vmcnt(21)
	v_pk_add_f32 v[92:93], v[92:93], v[178:179]
	v_pk_add_f32 v[94:95], v[94:95], v[180:181]
	global_store_dwordx4 v141, v[92:95], s[28:29] offset:512
	global_load_dwordx4 v[178:181], v145, s[28:29] offset:512 nt
	s_waitcnt vmcnt(22)
	v_pk_add_f32 v[84:85], v[84:85], v[182:183]
	v_pk_add_f32 v[86:87], v[86:87], v[184:185]
	global_store_dwordx4 v141, v[84:87], s[28:29] offset:576
	global_load_dwordx4 v[182:185], v145, s[28:29] offset:576 nt
	s_waitcnt vmcnt(23)
	v_pk_add_f32 v[104:105], v[104:105], v[186:187]
	v_pk_add_f32 v[106:107], v[106:107], v[188:189]
	global_store_dwordx4 v142, v[104:107], s[28:29]
	global_load_dwordx4 v[186:189], v150, s[28:29] nt
	s_waitcnt vmcnt(24)
	v_pk_add_f32 v[96:97], v[96:97], v[190:191]
	v_pk_add_f32 v[98:99], v[98:99], v[192:193]
	global_store_dwordx4 v142, v[96:99], s[28:29] offset:64
	global_load_dwordx4 v[190:193], v150, s[28:29] offset:64 nt
	s_waitcnt vmcnt(25)
	v_pk_add_f32 v[76:77], v[76:77], v[194:195]
	v_pk_add_f32 v[78:79], v[78:79], v[196:197]
	global_store_dwordx4 v142, v[76:79], s[28:29] offset:512
	global_load_dwordx4 v[194:197], v150, s[28:29] offset:512 nt
	s_waitcnt vmcnt(26)
;     __device__ __forceinline__ void operator()(const f32x4 (&acc)[2][2][4][2], const Unit& u, int wr, int wc, int fr, int fq) const {
;     ...
;             for (int m = 0; m < 4; ++m)
; #pragma unroll
;                 for (int bj = 0; bj < 2; ++bj)
; #pragma unroll
;                     for (int n = 0; n < 2; ++n) b[m][bj][n] = __builtin_nontemporal_load((const f32x4*)(base + (size_t)(row0 + ai * HALF + m * 16) * ldc + c0 + bj * HALF + n * 16));
; #pragma unroll
;             for (int m = 0; m < 4; ++m) {
;                 const size_t off = (size_t)(row0 + ai * HALF + m * 16) * ldc + c0;
; #pragma unroll
;                 for (int bj = 0; bj < 2; ++bj)
; #pragma unroll
;                     for (int n = 0; n < 2; ++n) {
;                         if (nt_store) __builtin_nontemporal_store(b[m][bj][n] + acc[ai][bj][m][n], (f32x4*)(out + off + bj * HALF + n * 16));
;                         else *(f32x4*)(out + off + bj * HALF + n * 16) = b[m][bj][n] + acc[ai][bj][m][n]; }
	v_pk_add_f32 v[72:73], v[72:73], v[198:199]
	v_pk_add_f32 v[74:75], v[74:75], v[200:201]
	global_store_dwordx4 v142, v[72:75], s[28:29] offset:576
	global_load_dwordx4 v[198:201], v150, s[28:29] offset:576 nt
	s_waitcnt vmcnt(27)
	v_pk_add_f32 v[88:89], v[88:89], v[202:203]
	v_pk_add_f32 v[90:91], v[90:91], v[204:205]
	global_store_dwordx4 v143, v[88:91], s[28:29]
	global_load_dwordx4 v[202:205], v151, s[28:29] nt
	s_waitcnt vmcnt(28)
	v_pk_add_f32 v[80:81], v[80:81], v[206:207]
	v_pk_add_f32 v[82:83], v[82:83], v[208:209]
	global_store_dwordx4 v143, v[80:83], s[28:29] offset:64
	global_load_dwordx4 v[206:209], v151, s[28:29] offset:64 nt
	s_waitcnt vmcnt(29)
	v_pk_add_f32 v[68:69], v[68:69], v[210:211]
	v_pk_add_f32 v[70:71], v[70:71], v[212:213]
	global_store_dwordx4 v143, v[68:71], s[28:29] offset:512
	global_load_dwordx4 v[210:213], v151, s[28:29] offset:512 nt
	s_waitcnt vmcnt(30)
	v_pk_add_f32 v[64:65], v[64:65], v[214:215]
	v_pk_add_f32 v[66:67], v[66:67], v[216:217]
	global_store_dwordx4 v143, v[64:67], s[28:29] offset:576
	global_load_dwordx4 v[214:217], v151, s[28:29] offset:576 nt
	s_waitcnt vmcnt(30)
	v_pk_add_f32 v[60:61], v[60:61], v[146:147]
	v_pk_add_f32 v[62:63], v[62:63], v[148:149]
	global_store_dwordx4 v144, v[60:63], s[28:29]
	s_waitcnt vmcnt(29)
	v_pk_add_f32 v[56:57], v[56:57], v[158:159]
	v_pk_add_f32 v[58:59], v[58:59], v[160:161]
	global_store_dwordx4 v144, v[56:59], s[28:29] offset:64
	s_waitcnt vmcnt(28)
	v_pk_add_f32 v[48:49], v[48:49], v[162:163]
	v_pk_add_f32 v[50:51], v[50:51], v[164:165]
	global_store_dwordx4 v144, v[48:51], s[28:29] offset:512
	s_waitcnt vmcnt(27)
	v_pk_add_f32 v[40:41], v[40:41], v[166:167]
	v_pk_add_f32 v[42:43], v[42:43], v[168:169]
	global_store_dwordx4 v144, v[40:43], s[28:29] offset:576
	s_waitcnt vmcnt(26)
	v_pk_add_f32 v[52:53], v[52:53], v[170:171]
	v_pk_add_f32 v[54:55], v[54:55], v[172:173]
	global_store_dwordx4 v145, v[52:55], s[28:29]
	s_waitcnt vmcnt(25)
	v_pk_add_f32 v[44:45], v[44:45], v[174:175]
	v_pk_add_f32 v[46:47], v[46:47], v[176:177]
	global_store_dwordx4 v145, v[44:47], s[28:29] offset:64
	s_waitcnt vmcnt(24)
	v_pk_add_f32 v[32:33], v[32:33], v[178:179]
	v_pk_add_f32 v[34:35], v[34:35], v[180:181]
	global_store_dwordx4 v145, v[32:35], s[28:29] offset:512
	s_waitcnt vmcnt(23)
	v_pk_add_f32 v[24:25], v[24:25], v[182:183]
	v_pk_add_f32 v[26:27], v[26:27], v[184:185]
	global_store_dwordx4 v145, v[24:27], s[28:29] offset:576
	s_waitcnt vmcnt(22)
	v_pk_add_f32 v[36:37], v[36:37], v[186:187]
	v_pk_add_f32 v[38:39], v[38:39], v[188:189]
	global_store_dwordx4 v150, v[36:39], s[28:29]
	s_waitcnt vmcnt(21)
	v_pk_add_f32 v[28:29], v[28:29], v[190:191]
	v_pk_add_f32 v[30:31], v[30:31], v[192:193]
	global_store_dwordx4 v150, v[28:31], s[28:29] offset:64
	s_waitcnt vmcnt(20)
	v_pk_add_f32 v[16:17], v[16:17], v[194:195]
	v_pk_add_f32 v[18:19], v[18:19], v[196:197]
	global_store_dwordx4 v150, v[16:19], s[28:29] offset:512
	s_waitcnt vmcnt(19)
	v_pk_add_f32 v[8:9], v[8:9], v[198:199]
	v_pk_add_f32 v[10:11], v[10:11], v[200:201]
	global_store_dwordx4 v150, v[8:11], s[28:29] offset:576
	s_waitcnt vmcnt(18)
	v_pk_add_f32 v[20:21], v[20:21], v[202:203]
	v_pk_add_f32 v[22:23], v[22:23], v[204:205]
	global_store_dwordx4 v151, v[20:23], s[28:29]
	s_waitcnt vmcnt(17)
	v_pk_add_f32 v[12:13], v[12:13], v[206:207]
	v_pk_add_f32 v[14:15], v[14:15], v[208:209]
	global_store_dwordx4 v151, v[12:15], s[28:29] offset:64
	s_waitcnt vmcnt(16)
	v_pk_add_f32 v[4:5], v[4:5], v[210:211]
	v_pk_add_f32 v[6:7], v[6:7], v[212:213]
	global_store_dwordx4 v151, v[4:7], s[28:29] offset:512
	s_waitcnt vmcnt(15)
	v_pk_add_f32 v[0:1], v[0:1], v[214:215]
	v_pk_add_f32 v[2:3], v[2:3], v[216:217]
	global_store_dwordx4 v151, v[0:3], s[28:29] offset:576
	s_mov_b64 s[24:25], -1
	s_and_b64 vcc, exec, s[0:1]
	s_cbranch_vccnz .LBB0_1086
	s_andn2_b64 vcc, exec, s[10:11]
	s_cbranch_vccnz .LBB0_1085
	s_barrier
	s_branch .LBB0_1085
